# GEMM_IN k-loop start offset also depends on the XCD id
# speedup vs baseline: 1.4316x; 1.0152x over previous
.LBB0_271:
	v_and_b32_e32 v150, 63, v128
	v_lshrrev_b32_e32 v151, 6, v128
	v_lshrrev_b32_e32 v152, 3, v150
	v_readfirstlane_b32 s0, v151
	v_and_b32_e32 v153, 7, v150
	v_xor_b32_e32 v153, v153, v152
	v_lshlrev_b32_e32 v153, 4, v153
	v_lshl_add_u32 v153, v152, 11, v153
	s_lshl_b32 s1, s0, 16
	v_add_u32_e32 v132, s1, v153
	v_add_u32_e32 v133, 0x3c00, v132
	v_add_u32_e32 v134, 0x7800, v132
	v_add_u32_e32 v135, 0xb400, v132
	s_lshl_b32 s1, s0, 12
	s_add_u32 s5, s1, 0
	s_add_u32 s6, s1, 16384
	s_add_u32 s7, s1, 45056
	s_add_u32 s8, s1, 61440
	v_and_b32_e32 v152, 15, v150
	v_lshrrev_b32_e32 v153, 4, v150
	v_and_b32_e32 v154, 7, v152
	v_xor_b32_e32 v154, v154, v153
	v_lshlrev_b32_e32 v154, 4, v154
	v_lshl_add_u32 v154, v152, 7, v154
	s_lshr_b32 s1, s0, 1
	s_lshl_b32 s1, s1, 13
	v_add_u32_e32 v136, s1, v154
	v_xor_b32_e32 v137, 64, v136
	v_add_u32_e32 v138, 0xb000, v136
	v_add_u32_e32 v139, 0xb000, v137
	s_and_b32 s1, s0, 1
	s_lshl_b32 s1, s1, 13
	s_add_u32 s1, s1, 16384
	v_add_u32_e32 v140, s1, v154
	v_xor_b32_e32 v141, 64, v140
	v_add_u32_e32 v142, 0xb000, v140
	v_add_u32_e32 v143, 0xb000, v141
	s_and_b32 s1, s0, 1
	s_lshl_b32 s1, s1, 6
	v_add_u32_e32 v152, s1, v152
	v_mov_b32_e32 v154, 0x4a00
	v_mul_lo_u32 v152, v152, v154
	v_lshlrev_b32_e32 v153, 3, v153
	s_lshr_b32 s1, s0, 1
	s_lshl_b32 s1, s1, 7
	v_add3_u32 v146, v152, v153, s1
	v_add_u32_e32 v147, 0x4a000, v146
	v_add_u32_e32 v148, 0x94000, v146
	v_add_u32_e32 v149, 0xde000, v146
	v_readlane_b32 s25, v252, 0
	v_readlane_b32 s98, v252, 0
	s_and_b32 s99, s98, 7
	s_lshr_b32 s98, s98, 3
	s_lshl_b32 s99, s99, 1
	s_add_i32 s98, s98, s99
	s_and_b32 s98, s98, 15
	s_and_b32 s0, s25, 63
	s_lshr_b32 s1, s25, 6
	s_mul_i32 s4, s70, 0x1280000
	s_lshl_b32 s39, s1, 18
	s_add_u32 s4, s4, s39
	s_add_u32 s26, s96, s4
	s_addc_u32 s27, s97, 0
	s_lshl_b32 s4, s0, 18
	s_add_u32 s4, s4, 0x82a6100
	s_add_u32 s28, s96, s4
	s_addc_u32 s29, s97, 0
	s_lshl_b32 s0, s98, 7
	s_add_u32 s26, s26, s0
	s_addc_u32 s27, s27, 0
	s_add_u32 s28, s28, s0
	s_addc_u32 s29, s29, 0
	s_mov_b32 s99, s98
	s_mov_b32 m0, s5
	s_nop 0
	global_load_lds_dwordx4 v132, s[26:27] offset:0
	global_load_lds_dwordx4 v133, s[26:27] offset:1024
	global_load_lds_dwordx4 v134, s[26:27] offset:2048
	global_load_lds_dwordx4 v135, s[26:27] offset:3072
	s_mov_b32 m0, s6
	s_nop 0
	global_load_lds_dwordx4 v132, s[28:29] offset:0
	global_load_lds_dwordx4 v133, s[28:29] offset:1024
	global_load_lds_dwordx4 v134, s[28:29] offset:2048
	global_load_lds_dwordx4 v135, s[28:29] offset:3072
	s_waitcnt vmcnt(0)
